# layer-1 w_in shift-bias tasks moved from the ffn_out(l0) prologue into ffn_in(l0) on the 64 workgroups that convert w_in[1], behind a 64-workgroup counter barrier (grid 256 only)
# speedup vs baseline: 1.0076x; 1.0076x over previous
.Lsb_exit:
	s_cmpk_lg_i32 s68, 0x100
	s_cbranch_scc1 .LBB0_171
	s_waitcnt vmcnt(0) lgkmcnt(0)
	s_barrier
	v_readfirstlane_b32 s0, v228
	s_nop 3
	s_cmp_lt_u32 s0, 64
	s_cbranch_scc0 .Lsb_join
	s_mov_b64 s[0:1], exec
	s_mov_b64 exec, 1
	v_mov_b32_e32 v0, 0x3580
	s_nop 1
	global_atomic_add v0, v249, s[88:89]
	s_mov_b32 s2, 0
.Lsb_poll:
	global_load_dword v1, v0, s[88:89] sc1
	s_waitcnt vmcnt(0)
	v_readfirstlane_b32 s3, v1
	s_nop 3
	s_cmp_ge_u32 s3, 64
	s_cbranch_scc1 .Lsb_done
	s_sleep 1
	s_add_u32 s2, s2, 1
	s_cmp_lt_u32 s2, 0x4000
	s_cbranch_scc1 .Lsb_poll
.Lsb_done:
	buffer_inv sc1
	s_waitcnt vmcnt(0)
	s_mov_b64 exec, s[0:1]
.Lsb_join:
	s_waitcnt vmcnt(0) lgkmcnt(0)
	s_barrier
	s_sub_i32 s28, s30, 0xc0
	s_lshl_b32 s28, s28, 1
	s_add_i32 s28, s28, s90
	s_cmpk_gt_i32 s28, 0x57
	s_cbranch_scc1 .LBB0_171
	s_or_b32 s28, s28, 0x900
	s_branch .Lbias_task
.Lbias_ret2:
	s_branch .LBB0_171
.LBB0_171:
	s_mov_b64 s[0:1], 0

.Lbias_col0:
	v_lshlrev_b32_e32 v162, 2, v162
	v_add_u32_e32 v163, s46, v162
	v_add_u32_e32 v164, s46, v163
	v_add_u32_e32 v165, s46, v164
	v_add_u32_e32 v166, s46, v165
	v_and_b32_e32 v160, 15, v160
	v_cmp_eq_u32_e64 s[52:53], 0, v160
	s_nop 4
	s_and_b64 exec, exec, s[52:53]
	global_store_dword v162, v80, s[44:45] sc1
	global_store_dword v162, v88, s[44:45] offset:4 sc1
	global_store_dword v163, v81, s[44:45] sc1
	global_store_dword v163, v89, s[44:45] offset:4 sc1
	global_store_dword v164, v82, s[44:45] sc1
	global_store_dword v164, v90, s[44:45] offset:4 sc1
	global_store_dword v165, v83, s[44:45] sc1
	global_store_dword v165, v91, s[44:45] offset:4 sc1
	global_store_dword v166, v84, s[44:45] sc1
	global_store_dword v166, v92, s[44:45] offset:4 sc1
	s_mov_b64 exec, s[50:51]
	s_add_i32 s54, s54, s70
	s_cmp_lt_i32 s54, s55
	s_cbranch_scc1 .Lbias_again
	v_mul_u32_u24_e32 v0, 0xc0, v228
	ds_read_b128 v[128:131], v0 offset:0
	ds_read_b128 v[132:135], v0 offset:16
	ds_read_b128 v[136:139], v0 offset:32
	ds_read_b128 v[140:143], v0 offset:48
	ds_read_b128 v[144:147], v0 offset:64
	ds_read_b128 v[148:151], v0 offset:80
	ds_read_b128 v[152:155], v0 offset:96
	ds_read_b128 v[156:159], v0 offset:112
	ds_read_b128 v[160:163], v0 offset:128
	ds_read_b128 v[164:167], v0 offset:144
	ds_read_b128 v[168:171], v0 offset:160
	ds_read_b128 v[172:175], v0 offset:176
	s_mov_b32 s28, s49
	v_readlane_b32 s40, v255, 42
	v_readlane_b32 s41, v255, 43
	v_readlane_b32 s42, v255, 44
	v_readlane_b32 s43, v255, 45
	v_readlane_b32 s44, v255, 46
	v_readlane_b32 s45, v255, 47
	v_readlane_b32 s46, v255, 48
	v_readlane_b32 s47, v255, 49
	v_readlane_b32 s48, v255, 50
	v_readlane_b32 s49, v255, 51
	v_readlane_b32 s50, v255, 52
	v_readlane_b32 s51, v255, 53
	v_readlane_b32 s52, v255, 54
	v_readlane_b32 s53, v255, 55
	v_readlane_b32 s54, v255, 56
	v_readlane_b32 s55, v255, 57
	s_waitcnt lgkmcnt(0)
	s_nop 3
	s_cmp_eq_u32 s28, 1
	s_cbranch_scc1 .Lbias_ret1
	s_cmp_eq_u32 s28, 2
	s_cbranch_scc1 .Lbias_ret2
	s_cmp_eq_u32 s28, 0
	s_cbranch_scc1 .Lbias_ret4
	s_branch .Lbias_ret3
.LBB0_286:
.LBB0_291:
	s_cmpk_gt_i32 s30, 0xff
	s_cbranch_scc1 .LBB0_385
	v_readlane_b32 s2, v255, 36
	s_lshl_b32 s0, s2, 3
	s_lshl_b32 s46, s90, 2
	s_add_i32 s47, s46, s0
	s_sub_i32 s33, 1, s90
	s_add_i32 s48, s47, -16
	s_cmp_eq_u32 s90, 0
	s_cselect_b64 s[36:37], -1, 0
	s_and_b64 s[0:1], s[36:37], exec
	s_movk_i32 s0, 0x500
	s_mul_i32 s33, s33, 0x12000
	s_cselect_b32 s49, s0, 0x700
	s_add_i32 s50, s69, 0x9000
	s_add_i32 s51, s69, 0x4800
	s_mov_b32 s52, s30
	s_mov_b32 s53, s30
	v_readlane_b32 s3, v255, 37
	s_branch .LBB0_294

.LBB0_558:
	s_nop 0
	v_readlane_b32 s0, v255, 39
	v_readlane_b32 s1, v255, 40
	s_and_b64 vcc, exec, s[0:1]
	s_cbranch_vccz .LBB0_677
	s_add_i32 s0, s74, 3
	s_cmp_lt_u32 s0, 11
	v_readlane_b32 s0, v255, 34
	s_cselect_b64 s[2:3], -1, 0
	s_cmpk_lt_i32 s0, 0x58
	s_cselect_b64 s[0:1], -1, 0
	s_and_b64 s[0:1], s[2:3], s[0:1]
	s_andn2_b64 vcc, exec, s[0:1]
	s_cbranch_vccnz .LBB0_564
	s_cmpk_eq_i32 s68, 0x100
	s_cbranch_scc1 .LBB0_564
	v_readlane_b32 s28, v255, 34
	s_nop 3
	s_or_b32 s28, s28, 0xd00
	s_branch .Lbias_task
